# NA: relative-position bias reads batched (no exec-masked branches); running-max row reduction via v_permlane16/32_swap instead of ds_bpermute
# speedup vs baseline: 1.0927x; 1.0116x over previous
.LBB0_340:
	s_cmp_gt_u32 s91, 3
	s_cselect_b64 vcc, -1, 0
	s_waitcnt lgkmcnt(0)
	v_cndmask_b32_e64 v79, v126, 0, vcc
	v_add_u32_e32 v0, v79, v129
	v_mad_u32_u24 v0, v0, s83, v155
	ds_read_b128 v[68:71], v0 offset:9216
	ds_read_b128 v[72:75], v0 offset:9280
	ds_read_b128 v[80:83], v0 offset:11520
	ds_read_b128 v[84:87], v0 offset:11584
	v_lshl_add_u32 v0, s91, 1, v163
	s_or_b64 s[34:35], vcc, s[36:37]
	s_waitcnt lgkmcnt(3)
	v_mfma_f32_16x16x32_bf16 v[68:71], v[68:71], v[40:43], 0
	v_mul_lo_u32 v2, v0, 31
	s_nor_b64 s[56:57], s[34:35], s[4:5]
	s_waitcnt lgkmcnt(1)
	v_mfma_f32_16x16x32_bf16 v[80:83], v[80:83], v[40:43], 0
	v_mfma_f32_16x16x32_bf16 v[72:75], v[72:75], v[36:39], v[68:71]
	s_waitcnt lgkmcnt(0)
	v_mfma_f32_16x16x32_bf16 v[68:71], v[84:87], v[36:39], v[80:83]
	s_nop 5
	s_or_b64 s[34:35], vcc, s[6:7]
	s_nor_b64 s[58:59], s[34:35], s[8:9]
	s_or_b64 s[34:35], vcc, s[10:11]
	s_nor_b64 s[60:61], s[34:35], s[12:13]
	s_or_b64 s[34:35], vcc, s[14:15]
	s_nor_b64 s[62:63], s[34:35], s[16:17]
	s_or_b64 s[34:35], vcc, s[18:19]
	s_nor_b64 s[64:65], s[34:35], s[0:1]
	s_or_b64 s[34:35], vcc, s[20:21]
	s_nor_b64 s[66:67], s[34:35], s[22:23]
	s_or_b64 s[34:35], vcc, s[24:25]
	s_nor_b64 s[68:69], s[34:35], s[26:27]
	s_or_b64 s[34:35], vcc, s[28:29]
	s_nor_b64 s[70:71], s[34:35], s[30:31]
	v_lshl_add_u32 v240, v2, 2, v140
	v_lshl_add_u32 v241, v2, 2, v141
	v_lshl_add_u32 v242, v2, 2, v142
	v_lshl_add_u32 v243, v2, 2, v143
	v_lshl_add_u32 v244, v2, 2, v144
	v_lshl_add_u32 v245, v2, 2, v145
	v_lshl_add_u32 v246, v2, 2, v146
	v_lshl_add_u32 v247, v2, 2, v148
	ds_read_b32 v240, v240 offset:45056
	ds_read_b32 v241, v241 offset:45056
	ds_read_b32 v242, v242 offset:45056
	ds_read_b32 v243, v243 offset:45056
	ds_read_b32 v244, v244 offset:45056
	ds_read_b32 v245, v245 offset:45056
	ds_read_b32 v246, v246 offset:45056
	ds_read_b32 v247, v247 offset:45056
	s_waitcnt lgkmcnt(0)
	v_add_f32_e32 v240, v72, v240
	v_add_f32_e32 v241, v73, v241
	v_add_f32_e32 v242, v74, v242
	v_add_f32_e32 v243, v75, v243
	v_add_f32_e32 v244, v68, v244
	v_add_f32_e32 v245, v69, v245
	v_add_f32_e32 v246, v70, v246
	v_add_f32_e32 v247, v71, v247
	v_cndmask_b32_e32 v76, v151, v72, vcc
	v_cndmask_b32_e64 v76, v76, v240, s[56:57]
	v_cndmask_b32_e32 v72, v151, v73, vcc
	v_cndmask_b32_e64 v72, v72, v241, s[58:59]
	v_cndmask_b32_e32 v73, v151, v74, vcc
	v_cndmask_b32_e64 v73, v73, v242, s[60:61]
	v_cndmask_b32_e32 v74, v151, v75, vcc
	v_cndmask_b32_e64 v74, v74, v243, s[62:63]
	v_cndmask_b32_e32 v75, v151, v68, vcc
	v_cndmask_b32_e64 v75, v75, v244, s[64:65]
	v_cndmask_b32_e32 v68, v151, v69, vcc
	v_cndmask_b32_e64 v68, v68, v245, s[66:67]
	v_cndmask_b32_e32 v69, v151, v70, vcc
	v_cndmask_b32_e64 v69, v69, v246, s[68:69]
	v_cndmask_b32_e32 v70, v151, v71, vcc
	v_cndmask_b32_e64 v70, v70, v247, s[70:71]
	v_max3_f32 v0, v76, s88, v72
	v_max3_f32 v0, v0, v73, v74
	v_max3_f32 v0, v0, v75, v68
	v_max3_f32 v0, v0, v69, v70
	v_mov_b32_e32 v3, v0
	s_nop 1
	v_permlane16_swap_b32_e32 v0, v3
	v_cmp_lt_f32_e64 s[34:35], s89, v76
	v_lshl_add_u32 v79, v79, 1, v139
	v_add_u32_e32 v85, 0x8800, v79
	ds_read2_b64 v[90:93], v85 offset0:192 offset1:196
	s_waitcnt lgkmcnt(0)
	v_max_f32_e32 v3, v3, v3
	v_max_f32_e32 v0, v0, v3
	v_mov_b32_e32 v3, v0
	s_nop 1
	v_permlane32_swap_b32_e32 v0, v3
	s_waitcnt lgkmcnt(0)
	v_max3_f32 v3, v165, v0, v3
	v_sub_f32_e32 v71, v76, v3
	v_exp_f32_e32 v71, v71
	v_sub_f32_e32 v77, v72, v3
	v_sub_f32_e32 v78, v73, v3
	v_exp_f32_e32 v77, v77
	v_sub_f32_e32 v80, v74, v3
	v_exp_f32_e32 v78, v78
	v_exp_f32_e32 v80, v80
	v_cndmask_b32_e64 v81, 0, v71, s[34:35]
	v_sub_f32_e32 v71, v75, v3
	v_cmp_lt_f32_e64 s[34:35], s89, v72
	v_exp_f32_e32 v71, v71
	v_sub_f32_e32 v72, v68, v3
	v_cndmask_b32_e64 v76, 0, v77, s[34:35]
	v_cmp_lt_f32_e64 s[34:35], s89, v73
	v_exp_f32_e32 v72, v72
	v_sub_f32_e32 v0, v165, v3
	v_cndmask_b32_e64 v77, 0, v78, s[34:35]
	v_cmp_lt_f32_e64 s[34:35], s89, v74
	v_exp_f32_e32 v0, v0
	v_add_u32_e32 v74, 0x7800, v79
	v_cndmask_b32_e64 v78, 0, v80, s[34:35]
	v_cmp_lt_f32_e64 s[34:35], s89, v75
	ds_read2_b64 v[86:89], v74 offset0:160 offset1:164
	v_pk_mul_f32 v[66:67], v[66:67], v[0:1] op_sel_hi:[1,0]
	v_cndmask_b32_e64 v82, 0, v71, s[34:35]
	v_cmp_lt_f32_e64 s[34:35], s89, v68
	v_sub_f32_e32 v68, v69, v3
	v_exp_f32_e32 v68, v68
	v_sub_f32_e32 v71, v70, v3
	v_exp_f32_e32 v71, v71
	v_cndmask_b32_e64 v80, 0, v72, s[34:35]
	v_cmp_lt_f32_e64 s[34:35], s89, v69
	v_pk_mul_f32 v[64:65], v[64:65], v[0:1] op_sel_hi:[1,0]
	v_cvt_pk_bf16_f32 v72, v81, v76
	v_cndmask_b32_e64 v83, 0, v68, s[34:35]
	v_cmp_lt_f32_e64 s[34:35], s89, v70
	v_add_u32_e32 v68, 0x6800, v79
	v_cvt_pk_bf16_f32 v73, v77, v78
	v_cndmask_b32_e64 v84, 0, v71, s[34:35]
	ds_read2_b64 v[68:71], v68 offset0:128 offset1:132
	v_cvt_pk_bf16_f32 v74, v82, v80
	v_cvt_pk_bf16_f32 v75, v83, v84
	v_pk_mul_f32 v[62:63], v[62:63], v[0:1] op_sel_hi:[1,0]
	v_pk_mul_f32 v[60:61], v[60:61], v[0:1] op_sel_hi:[1,0]
	s_waitcnt lgkmcnt(0)
	v_mfma_f32_16x16x32_bf16 v[64:67], v[68:71], v[72:75], v[64:67]
	v_add_u32_e32 v68, 0x9800, v79
	ds_read2_b64 v[68:71], v68 offset0:224 offset1:228
	v_cndmask_b32_e64 v79, v137, 32, vcc
	v_add_u32_e32 v85, v79, v129
	v_mad_u32_u24 v85, v85, s83, v155
	v_mfma_f32_16x16x32_bf16 v[60:63], v[86:89], v[72:75], v[60:63]
	ds_read_b128 v[86:89], v85 offset:9216
	v_pk_mul_f32 v[54:55], v[54:55], v[0:1] op_sel_hi:[1,0]
	v_pk_mul_f32 v[52:53], v[52:53], v[0:1] op_sel_hi:[1,0]
	v_pk_mul_f32 v[58:59], v[58:59], v[0:1] op_sel_hi:[1,0]
	v_pk_mul_f32 v[56:57], v[56:57], v[0:1] op_sel_hi:[1,0]
	s_waitcnt lgkmcnt(1)
	v_mfma_f32_16x16x32_bf16 v[52:55], v[68:71], v[72:75], v[52:55]
	ds_read_b128 v[68:71], v85 offset:9280
	v_mfma_f32_16x16x32_bf16 v[56:59], v[90:93], v[72:75], v[56:59]
	s_waitcnt lgkmcnt(1)
	v_mfma_f32_16x16x32_bf16 v[72:75], v[86:89], v[40:43], 0
	ds_read_b128 v[86:89], v85 offset:11520
	s_waitcnt lgkmcnt(1)
	v_mfma_f32_16x16x32_bf16 v[72:75], v[68:71], v[36:39], v[72:75]
	ds_read_b128 v[68:71], v85 offset:11584
	s_waitcnt lgkmcnt(1)
	v_mfma_f32_16x16x32_bf16 v[86:89], v[86:89], v[40:43], 0
	s_nop 4
	s_waitcnt lgkmcnt(0)
	v_mfma_f32_16x16x32_bf16 v[68:71], v[68:71], v[36:39], v[86:89]
	v_lshl_add_u32 v240, v2, 2, v140
	v_lshl_add_u32 v241, v2, 2, v141
	v_lshl_add_u32 v242, v2, 2, v142
	v_lshl_add_u32 v243, v2, 2, v143
	v_lshl_add_u32 v244, v2, 2, v144
	v_lshl_add_u32 v245, v2, 2, v145
	v_lshl_add_u32 v246, v2, 2, v146
	v_lshl_add_u32 v247, v2, 2, v148
	ds_read_b32 v240, v240 offset:45180
	ds_read_b32 v241, v241 offset:45180
	ds_read_b32 v242, v242 offset:45180
	ds_read_b32 v243, v243 offset:45180
	ds_read_b32 v244, v244 offset:45180
	ds_read_b32 v245, v245 offset:45180
	ds_read_b32 v246, v246 offset:45180
	ds_read_b32 v247, v247 offset:45180
	s_waitcnt lgkmcnt(0)
	v_add_f32_e32 v240, v72, v240
	v_add_f32_e32 v241, v73, v241
	v_add_f32_e32 v242, v74, v242
	v_add_f32_e32 v243, v75, v243
	v_add_f32_e32 v244, v68, v244
	v_add_f32_e32 v245, v69, v245
	v_add_f32_e32 v246, v70, v246
	v_add_f32_e32 v247, v71, v247
	v_cndmask_b32_e32 v85, v151, v72, vcc
	v_cndmask_b32_e64 v85, v85, v240, s[56:57]
	v_cndmask_b32_e32 v72, v151, v73, vcc
	v_cndmask_b32_e64 v72, v72, v241, s[58:59]
	v_cndmask_b32_e32 v73, v151, v74, vcc
	v_cndmask_b32_e64 v73, v73, v242, s[60:61]
	v_cndmask_b32_e32 v74, v151, v75, vcc
	v_cndmask_b32_e64 v74, v74, v243, s[62:63]
	v_cndmask_b32_e32 v75, v151, v68, vcc
	v_cndmask_b32_e64 v75, v75, v244, s[64:65]
	v_cndmask_b32_e32 v68, v151, v69, vcc
	v_cndmask_b32_e64 v68, v68, v245, s[66:67]
	v_cndmask_b32_e32 v69, v151, v70, vcc
	v_cndmask_b32_e64 v69, v69, v246, s[68:69]
	v_cndmask_b32_e32 v70, v151, v71, vcc
	v_cndmask_b32_e64 v70, v70, v247, s[70:71]
.LBB0_365:
	v_max3_f32 v2, v85, s88, v72
	v_max3_f32 v2, v2, v73, v74
	v_max3_f32 v2, v2, v75, v68
	v_max3_f32 v2, v2, v69, v70
	v_add_f32_e32 v71, 0, v81
	v_mov_b32_e32 v81, v2
	s_nop 1
	v_permlane16_swap_b32_e32 v2, v81
	v_add_f32_e32 v71, v76, v71
	v_add_f32_e32 v71, v77, v71
	v_add_f32_e32 v71, v78, v71
	v_add_f32_e32 v71, v82, v71
	s_waitcnt lgkmcnt(0)
	v_max_f32_e32 v76, v81, v81
	v_max_f32_e32 v2, v2, v76
	v_mov_b32_e32 v76, v2
	s_nop 1
	v_permlane32_swap_b32_e32 v2, v76
	v_add_f32_e32 v71, v80, v71
	v_add_f32_e32 v71, v83, v71
	v_add_f32_e32 v84, v84, v71
	v_fmac_f32_e32 v84, v164, v0
	s_waitcnt lgkmcnt(0)
	v_max3_f32 v165, v3, v2, v76
	v_sub_f32_e32 v2, v85, v165
	v_exp_f32_e32 v2, v2
	v_sub_f32_e32 v0, v3, v165
	v_sub_f32_e32 v3, v72, v165
	v_cmp_lt_f32_e64 s[34:35], s89, v85
	v_exp_f32_e32 v3, v3
	v_sub_f32_e32 v76, v74, v165
	v_cndmask_b32_e64 v2, 0, v2, s[34:35]
	v_cmp_lt_f32_e64 s[34:35], s89, v72
	v_sub_f32_e32 v72, v73, v165
	v_exp_f32_e32 v72, v72
	v_exp_f32_e32 v76, v76
	v_add_f32_e32 v71, 0, v2
	v_cndmask_b32_e64 v3, 0, v3, s[34:35]
	v_cmp_lt_f32_e64 s[34:35], s89, v73
	v_add_f32_e32 v71, v3, v71
	v_lshl_add_u32 v90, v79, 1, v139
	v_cndmask_b32_e64 v73, 0, v72, s[34:35]
	v_cmp_lt_f32_e64 s[34:35], s89, v74
	v_add_f32_e32 v71, v73, v71
	v_sub_f32_e32 v72, v68, v165
	v_cndmask_b32_e64 v74, 0, v76, s[34:35]
	v_add_f32_e32 v85, v74, v71
	v_sub_f32_e32 v71, v75, v165
	v_exp_f32_e32 v71, v71
	v_cmp_lt_f32_e64 s[34:35], s89, v75
	v_exp_f32_e32 v72, v72
	v_exp_f32_e32 v0, v0
	v_cndmask_b32_e64 v86, 0, v71, s[34:35]
	v_cmp_lt_f32_e64 s[34:35], s89, v68
	v_sub_f32_e32 v68, v69, v165
	v_exp_f32_e32 v68, v68
	v_sub_f32_e32 v71, v70, v165
	v_exp_f32_e32 v71, v71
	v_cndmask_b32_e64 v87, 0, v72, s[34:35]
	v_cmp_lt_f32_e64 s[34:35], s89, v69
	v_cvt_pk_bf16_f32 v72, v2, v3
	v_add_u32_e32 v2, 0x7800, v90
	v_cndmask_b32_e64 v88, 0, v68, s[34:35]
	v_cmp_lt_f32_e64 s[34:35], s89, v70
	v_add_u32_e32 v68, 0x6800, v90
	ds_read2_b64 v[76:79], v2 offset0:160 offset1:164
	v_cndmask_b32_e64 v89, 0, v71, s[34:35]
	ds_read2_b64 v[68:71], v68 offset0:128 offset1:132
	v_add_u32_e32 v2, 0x8800, v90
	v_pk_mul_f32 v[66:67], v[66:67], v[0:1] op_sel_hi:[1,0]
	v_pk_mul_f32 v[64:65], v[64:65], v[0:1] op_sel_hi:[1,0]
	v_cvt_pk_bf16_f32 v73, v73, v74
	v_cvt_pk_bf16_f32 v74, v86, v87
	v_cvt_pk_bf16_f32 v75, v88, v89
	ds_read2_b64 v[80:83], v2 offset0:192 offset1:196
	v_add_u32_e32 v2, 0x9800, v90
	s_waitcnt lgkmcnt(1)
	v_mfma_f32_16x16x32_bf16 v[64:67], v[68:71], v[72:75], v[64:67]
	ds_read2_b64 v[68:71], v2 offset0:224 offset1:228
	v_pk_mul_f32 v[62:63], v[62:63], v[0:1] op_sel_hi:[1,0]
	v_pk_mul_f32 v[60:61], v[60:61], v[0:1] op_sel_hi:[1,0]
	v_pk_mul_f32 v[58:59], v[58:59], v[0:1] op_sel_hi:[1,0]
	v_pk_mul_f32 v[56:57], v[56:57], v[0:1] op_sel_hi:[1,0]
	v_pk_mul_f32 v[54:55], v[54:55], v[0:1] op_sel_hi:[1,0]
	v_pk_mul_f32 v[52:53], v[52:53], v[0:1] op_sel_hi:[1,0]
	v_add_f32_e32 v2, v86, v85
	v_mfma_f32_16x16x32_bf16 v[60:63], v[76:79], v[72:75], v[60:63]
	v_add_f32_e32 v2, v87, v2
	v_add_f32_e32 v2, v88, v2
	v_add_f32_e32 v164, v89, v2
	s_waitcnt lgkmcnt(1)
	v_mfma_f32_16x16x32_bf16 v[56:59], v[80:83], v[72:75], v[56:59]
	v_cndmask_b32_e64 v2, 0, 1, vcc
	v_cmp_ne_u32_e64 s[34:35], 1, v2
	s_andn2_b64 vcc, exec, vcc
	s_waitcnt lgkmcnt(0)
	v_mfma_f32_16x16x32_bf16 v[52:55], v[68:71], v[72:75], v[52:55]
	v_fmac_f32_e32 v164, v84, v0
	s_cbranch_vccz .LBB0_376
	s_and_b64 vcc, exec, s[34:35]
	s_cbranch_vccnz .LBB0_325
	s_branch .LBB0_377

.LBB0_376:
	v_add_u32_e32 v0, v155, v138
	ds_read_b128 v[68:71], v0 offset:18432
	ds_read_b128 v[72:75], v0 offset:18496
	ds_read_b128 v[76:79], v0 offset:20736
	ds_read_b128 v[80:83], v0 offset:20800
	s_waitcnt lgkmcnt(3)
	v_mfma_f32_16x16x32_bf16 v[68:71], v[68:71], v[40:43], 0
	s_waitcnt lgkmcnt(1)
	v_mfma_f32_16x16x32_bf16 v[76:79], v[76:79], v[40:43], 0
	v_mfma_f32_16x16x32_bf16 v[68:71], v[72:75], v[36:39], v[68:71]
	s_waitcnt lgkmcnt(0)
	v_mfma_f32_16x16x32_bf16 v[72:75], v[80:83], v[36:39], v[76:79]
	s_nop 5
	v_max3_f32 v0, v68, s88, v69
	v_max3_f32 v0, v0, v70, v71
	v_max3_f32 v0, v0, v72, v73
	v_max3_f32 v0, v0, v74, v75
	v_mov_b32_e32 v2, v0
	s_nop 1
	v_permlane16_swap_b32_e32 v0, v2
	v_cmp_lt_f32_e32 vcc, s89, v68
	s_waitcnt lgkmcnt(0)
	v_max_f32_e32 v2, v2, v2
	v_max_f32_e32 v0, v0, v2
	v_mov_b32_e32 v2, v0
	s_nop 1
	v_permlane32_swap_b32_e32 v0, v2
	s_waitcnt lgkmcnt(0)
	v_max3_f32 v2, v165, v0, v2
	v_sub_f32_e32 v3, v68, v2
	v_sub_f32_e32 v76, v69, v2
	v_exp_f32_e32 v3, v3
	v_sub_f32_e32 v77, v70, v2
	v_exp_f32_e32 v76, v76
	v_sub_f32_e32 v78, v71, v2
	v_exp_f32_e32 v77, v77
	v_exp_f32_e32 v78, v78
	v_cndmask_b32_e32 v3, 0, v3, vcc
	v_cmp_lt_f32_e32 vcc, s89, v69
	v_add_f32_e32 v68, 0, v3
	v_sub_f32_e32 v79, v72, v2
	v_cndmask_b32_e32 v76, 0, v76, vcc
	v_cmp_lt_f32_e32 vcc, s89, v70
	v_add_f32_e32 v68, v76, v68
	v_sub_f32_e32 v80, v73, v2
	v_cndmask_b32_e32 v77, 0, v77, vcc
	v_cmp_lt_f32_e32 vcc, s89, v71
	v_exp_f32_e32 v79, v79
	v_add_f32_e32 v68, v77, v68
	v_cndmask_b32_e32 v78, 0, v78, vcc
	v_exp_f32_e32 v80, v80
	v_add_f32_e32 v84, v78, v68
	v_sub_f32_e32 v68, v74, v2
	v_exp_f32_e32 v68, v68
	v_sub_f32_e32 v69, v75, v2
	v_cmp_lt_f32_e32 vcc, s89, v72
	v_exp_f32_e32 v69, v69
	v_sub_f32_e32 v0, v165, v2
	v_cndmask_b32_e32 v85, 0, v79, vcc
	v_cmp_lt_f32_e32 vcc, s89, v73
	v_exp_f32_e32 v0, v0
	v_cvt_pk_bf16_f32 v72, v3, v76
	v_cndmask_b32_e32 v86, 0, v80, vcc
	v_cmp_lt_f32_e32 vcc, s89, v74
	v_add_u32_e32 v3, 0x7800, v139
	v_cvt_pk_bf16_f32 v73, v77, v78
	v_cndmask_b32_e32 v87, 0, v68, vcc
	v_cmp_lt_f32_e32 vcc, s89, v75
	v_add_u32_e32 v68, 0x6800, v139
	ds_read2_b64 v[76:79], v3 offset0:176 offset1:180
	v_cndmask_b32_e32 v88, 0, v69, vcc
	ds_read2_b64 v[68:71], v68 offset0:144 offset1:148
	v_add_u32_e32 v3, 0x8800, v139
	v_pk_mul_f32 v[66:67], v[66:67], v[0:1] op_sel_hi:[1,0]
	v_pk_mul_f32 v[64:65], v[64:65], v[0:1] op_sel_hi:[1,0]
	v_cvt_pk_bf16_f32 v74, v85, v86
	v_cvt_pk_bf16_f32 v75, v87, v88
	ds_read2_b64 v[80:83], v3 offset0:208 offset1:212
	v_add_u32_e32 v3, 0x9800, v139
	s_waitcnt lgkmcnt(1)
	v_mfma_f32_16x16x32_bf16 v[64:67], v[68:71], v[72:75], v[64:67]
	ds_read2_b64 v[68:71], v3 offset0:240 offset1:244
	v_add_f32_e32 v3, v85, v84
	v_pk_mul_f32 v[62:63], v[62:63], v[0:1] op_sel_hi:[1,0]
	v_pk_mul_f32 v[60:61], v[60:61], v[0:1] op_sel_hi:[1,0]
	v_pk_mul_f32 v[58:59], v[58:59], v[0:1] op_sel_hi:[1,0]
	v_pk_mul_f32 v[56:57], v[56:57], v[0:1] op_sel_hi:[1,0]
	v_pk_mul_f32 v[54:55], v[54:55], v[0:1] op_sel_hi:[1,0]
	v_pk_mul_f32 v[52:53], v[52:53], v[0:1] op_sel_hi:[1,0]
	v_add_f32_e32 v3, v86, v3
	v_mfma_f32_16x16x32_bf16 v[60:63], v[76:79], v[72:75], v[60:63]
	v_add_f32_e32 v3, v87, v3
	v_add_f32_e32 v3, v88, v3
	v_fmac_f32_e32 v3, v164, v0
	s_waitcnt lgkmcnt(1)
	v_mfma_f32_16x16x32_bf16 v[56:59], v[80:83], v[72:75], v[56:59]
	v_mov_b32_e32 v164, v3
	v_mov_b32_e32 v165, v2
	s_waitcnt lgkmcnt(0)
	v_mfma_f32_16x16x32_bf16 v[52:55], v[68:71], v[72:75], v[52:55]
	s_and_b64 vcc, exec, s[34:35]
	s_cbranch_vccnz .LBB0_325
.LBB0_377:
	v_add_u32_e32 v0, v155, v138
	ds_read_b128 v[68:71], v0 offset:23040
	ds_read_b128 v[72:75], v0 offset:23104
	ds_read_b128 v[76:79], v0 offset:25344
	ds_read_b128 v[80:83], v0 offset:25408
	s_waitcnt lgkmcnt(3)
	v_mfma_f32_16x16x32_bf16 v[68:71], v[68:71], v[40:43], 0
	s_waitcnt lgkmcnt(1)
	v_mfma_f32_16x16x32_bf16 v[76:79], v[76:79], v[40:43], 0
	v_mfma_f32_16x16x32_bf16 v[68:71], v[72:75], v[36:39], v[68:71]
	s_waitcnt lgkmcnt(0)
	v_mfma_f32_16x16x32_bf16 v[72:75], v[80:83], v[36:39], v[76:79]
	s_nop 5
	v_max3_f32 v0, v68, s88, v69
	v_max3_f32 v0, v0, v70, v71
	v_max3_f32 v0, v0, v72, v73
	v_max3_f32 v0, v0, v74, v75
	v_mov_b32_e32 v2, v0
	s_nop 1
	v_permlane16_swap_b32_e32 v0, v2
	v_cmp_lt_f32_e32 vcc, s89, v68
	s_waitcnt lgkmcnt(0)
	v_max_f32_e32 v2, v2, v2
	v_max_f32_e32 v0, v0, v2
	v_mov_b32_e32 v2, v0
	s_nop 1
	v_permlane32_swap_b32_e32 v0, v2
	s_waitcnt lgkmcnt(0)
	v_max3_f32 v2, v165, v0, v2
	v_sub_f32_e32 v3, v68, v2
	v_sub_f32_e32 v76, v69, v2
	v_exp_f32_e32 v3, v3
	v_sub_f32_e32 v77, v70, v2
	v_exp_f32_e32 v76, v76
	v_sub_f32_e32 v78, v71, v2
	v_exp_f32_e32 v77, v77
	v_exp_f32_e32 v78, v78
	v_cndmask_b32_e32 v3, 0, v3, vcc
	v_cmp_lt_f32_e32 vcc, s89, v69
	v_add_f32_e32 v68, 0, v3
	v_sub_f32_e32 v79, v72, v2
	v_cndmask_b32_e32 v76, 0, v76, vcc
	v_cmp_lt_f32_e32 vcc, s89, v70
	v_add_f32_e32 v68, v76, v68
	v_sub_f32_e32 v80, v73, v2
	v_cndmask_b32_e32 v77, 0, v77, vcc
	v_cmp_lt_f32_e32 vcc, s89, v71
	v_exp_f32_e32 v79, v79
	v_add_f32_e32 v68, v77, v68
	v_cndmask_b32_e32 v78, 0, v78, vcc
	v_exp_f32_e32 v80, v80
	v_add_f32_e32 v84, v78, v68
	v_sub_f32_e32 v68, v74, v2
	v_exp_f32_e32 v68, v68
	v_sub_f32_e32 v69, v75, v2
	v_cmp_lt_f32_e32 vcc, s89, v72
	v_exp_f32_e32 v69, v69
	v_sub_f32_e32 v0, v165, v2
	v_cndmask_b32_e32 v85, 0, v79, vcc
	v_cmp_lt_f32_e32 vcc, s89, v73
	v_exp_f32_e32 v0, v0
	v_cvt_pk_bf16_f32 v72, v3, v76
	v_cndmask_b32_e32 v86, 0, v80, vcc
	v_cmp_lt_f32_e32 vcc, s89, v74
	v_add_u32_e32 v3, 0x7800, v139
	v_cvt_pk_bf16_f32 v73, v77, v78
	v_cndmask_b32_e32 v87, 0, v68, vcc
	v_cmp_lt_f32_e32 vcc, s89, v75
	v_add_u32_e32 v68, 0x6800, v139
	ds_read2_b64 v[76:79], v3 offset0:184 offset1:188
	v_cndmask_b32_e32 v88, 0, v69, vcc
	ds_read2_b64 v[68:71], v68 offset0:152 offset1:156
	v_add_u32_e32 v3, 0x8800, v139
	v_pk_mul_f32 v[66:67], v[66:67], v[0:1] op_sel_hi:[1,0]
	v_pk_mul_f32 v[64:65], v[64:65], v[0:1] op_sel_hi:[1,0]
	v_cvt_pk_bf16_f32 v74, v85, v86
	v_cvt_pk_bf16_f32 v75, v87, v88
	ds_read2_b64 v[80:83], v3 offset0:216 offset1:220
	v_add_u32_e32 v3, 0x9800, v139
	s_waitcnt lgkmcnt(1)
	v_mfma_f32_16x16x32_bf16 v[64:67], v[68:71], v[72:75], v[64:67]
	ds_read2_b64 v[68:71], v3 offset0:248 offset1:252
	v_add_f32_e32 v3, v85, v84
	v_pk_mul_f32 v[62:63], v[62:63], v[0:1] op_sel_hi:[1,0]
	v_pk_mul_f32 v[60:61], v[60:61], v[0:1] op_sel_hi:[1,0]
	v_pk_mul_f32 v[58:59], v[58:59], v[0:1] op_sel_hi:[1,0]
	v_pk_mul_f32 v[56:57], v[56:57], v[0:1] op_sel_hi:[1,0]
	v_pk_mul_f32 v[54:55], v[54:55], v[0:1] op_sel_hi:[1,0]
	v_pk_mul_f32 v[52:53], v[52:53], v[0:1] op_sel_hi:[1,0]
	v_add_f32_e32 v3, v86, v3
	v_mfma_f32_16x16x32_bf16 v[60:63], v[76:79], v[72:75], v[60:63]
	v_add_f32_e32 v3, v87, v3
	v_add_f32_e32 v3, v88, v3
	v_fmac_f32_e32 v3, v164, v0
	s_waitcnt lgkmcnt(1)
	v_mfma_f32_16x16x32_bf16 v[56:59], v[80:83], v[72:75], v[56:59]
	v_mov_b32_e32 v164, v3
	v_mov_b32_e32 v165, v2
	s_waitcnt lgkmcnt(0)
	v_mfma_f32_16x16x32_bf16 v[52:55], v[68:71], v[72:75], v[52:55]
	s_branch .LBB0_325

.LBB0_424:
	s_cmp_gt_u32 s83, 3
	s_cselect_b64 vcc, -1, 0
	s_waitcnt lgkmcnt(0)
	v_cndmask_b32_e64 v79, v105, 0, vcc
	v_add_u32_e32 v0, v79, v129
	v_mad_u32_u24 v0, v0, s75, v155
	ds_read_b128 v[68:71], v0 offset:9216
	ds_read_b128 v[72:75], v0 offset:9280
	ds_read_b128 v[80:83], v0 offset:11520
	ds_read_b128 v[84:87], v0 offset:11584
	v_lshl_add_u32 v0, s83, 1, v151
	s_or_b64 s[34:35], vcc, s[36:37]
	s_waitcnt lgkmcnt(3)
	v_mfma_f32_16x16x32_bf16 v[68:71], v[68:71], v[40:43], 0
	v_mul_lo_u32 v2, v0, 31
	s_nor_b64 s[56:57], s[34:35], s[4:5]
	s_waitcnt lgkmcnt(1)
	v_mfma_f32_16x16x32_bf16 v[80:83], v[80:83], v[40:43], 0
	v_mfma_f32_16x16x32_bf16 v[72:75], v[72:75], v[36:39], v[68:71]
	s_waitcnt lgkmcnt(0)
	v_mfma_f32_16x16x32_bf16 v[68:71], v[84:87], v[36:39], v[80:83]
	s_nop 5
	s_or_b64 s[34:35], vcc, s[6:7]
	s_nor_b64 s[58:59], s[34:35], s[8:9]
	s_or_b64 s[34:35], vcc, s[10:11]
	s_nor_b64 s[60:61], s[34:35], s[12:13]
	s_or_b64 s[34:35], vcc, s[14:15]
	s_nor_b64 s[62:63], s[34:35], s[16:17]
	s_or_b64 s[34:35], vcc, s[18:19]
	s_nor_b64 s[64:65], s[34:35], s[0:1]
	s_or_b64 s[34:35], vcc, s[20:21]
	s_nor_b64 s[66:67], s[34:35], s[22:23]
	s_or_b64 s[34:35], vcc, s[24:25]
	s_nor_b64 s[68:69], s[34:35], s[26:27]
	s_or_b64 s[34:35], vcc, s[28:29]
	s_nor_b64 s[70:71], s[34:35], s[30:31]
	v_lshl_add_u32 v240, v2, 2, v137
	v_lshl_add_u32 v241, v2, 2, v138
	v_lshl_add_u32 v242, v2, 2, v139
	v_lshl_add_u32 v243, v2, 2, v140
	v_lshl_add_u32 v244, v2, 2, v141
	v_lshl_add_u32 v245, v2, 2, v142
	v_lshl_add_u32 v246, v2, 2, v143
	v_lshl_add_u32 v247, v2, 2, v144
	ds_read_b32 v240, v240 offset:45056
	ds_read_b32 v241, v241 offset:45056
	ds_read_b32 v242, v242 offset:45056
	ds_read_b32 v243, v243 offset:45056
	ds_read_b32 v244, v244 offset:45056
	ds_read_b32 v245, v245 offset:45056
	ds_read_b32 v246, v246 offset:45056
	ds_read_b32 v247, v247 offset:45056
	s_waitcnt lgkmcnt(0)
	v_add_f32_e32 v240, v72, v240
	v_add_f32_e32 v241, v73, v241
	v_add_f32_e32 v242, v74, v242
	v_add_f32_e32 v243, v75, v243
	v_add_f32_e32 v244, v68, v244
	v_add_f32_e32 v245, v69, v245
	v_add_f32_e32 v246, v70, v246
	v_add_f32_e32 v247, v71, v247
	v_cndmask_b32_e32 v76, v147, v72, vcc
	v_cndmask_b32_e64 v76, v76, v240, s[56:57]
	v_cndmask_b32_e32 v72, v147, v73, vcc
	v_cndmask_b32_e64 v72, v72, v241, s[58:59]
	v_cndmask_b32_e32 v73, v147, v74, vcc
	v_cndmask_b32_e64 v73, v73, v242, s[60:61]
	v_cndmask_b32_e32 v74, v147, v75, vcc
	v_cndmask_b32_e64 v74, v74, v243, s[62:63]
	v_cndmask_b32_e32 v75, v147, v68, vcc
	v_cndmask_b32_e64 v75, v75, v244, s[64:65]
	v_cndmask_b32_e32 v68, v147, v69, vcc
	v_cndmask_b32_e64 v68, v68, v245, s[66:67]
	v_cndmask_b32_e32 v69, v147, v70, vcc
	v_cndmask_b32_e64 v69, v69, v246, s[68:69]
	v_cndmask_b32_e32 v70, v147, v71, vcc
	v_cndmask_b32_e64 v70, v70, v247, s[70:71]
	v_max3_f32 v0, v76, s80, v72
	v_max3_f32 v0, v0, v73, v74
	v_max3_f32 v0, v0, v75, v68
	v_max3_f32 v0, v0, v69, v70
	v_mov_b32_e32 v3, v0
	s_nop 1
	v_permlane16_swap_b32_e32 v0, v3
	v_cmp_lt_f32_e64 s[34:35], s81, v76
	v_lshl_add_u32 v79, v79, 1, v136
	v_add_u32_e32 v85, 0x8800, v79
	ds_read2_b64 v[90:93], v85 offset0:192 offset1:196
	s_waitcnt lgkmcnt(0)
	v_max_f32_e32 v3, v3, v3
	v_max_f32_e32 v0, v0, v3
	v_mov_b32_e32 v3, v0
	s_nop 1
	v_permlane32_swap_b32_e32 v0, v3
	s_waitcnt lgkmcnt(0)
	v_max3_f32 v3, v153, v0, v3
	v_sub_f32_e32 v71, v76, v3
	v_exp_f32_e32 v71, v71
	v_sub_f32_e32 v77, v72, v3
	v_sub_f32_e32 v78, v73, v3
	v_exp_f32_e32 v77, v77
	v_sub_f32_e32 v80, v74, v3
	v_exp_f32_e32 v78, v78
	v_exp_f32_e32 v80, v80
	v_cndmask_b32_e64 v81, 0, v71, s[34:35]
	v_sub_f32_e32 v71, v75, v3
	v_cmp_lt_f32_e64 s[34:35], s81, v72
	v_exp_f32_e32 v71, v71
	v_sub_f32_e32 v72, v68, v3
	v_cndmask_b32_e64 v76, 0, v77, s[34:35]
	v_cmp_lt_f32_e64 s[34:35], s81, v73
	v_exp_f32_e32 v72, v72
	v_sub_f32_e32 v0, v153, v3
	v_cndmask_b32_e64 v77, 0, v78, s[34:35]
	v_cmp_lt_f32_e64 s[34:35], s81, v74
	v_exp_f32_e32 v0, v0
	v_add_u32_e32 v74, 0x7800, v79
	v_cndmask_b32_e64 v78, 0, v80, s[34:35]
	v_cmp_lt_f32_e64 s[34:35], s81, v75
	ds_read2_b64 v[86:89], v74 offset0:160 offset1:164
	v_pk_mul_f32 v[66:67], v[66:67], v[0:1] op_sel_hi:[1,0]
	v_cndmask_b32_e64 v82, 0, v71, s[34:35]
	v_cmp_lt_f32_e64 s[34:35], s81, v68
	v_sub_f32_e32 v68, v69, v3
	v_exp_f32_e32 v68, v68
	v_sub_f32_e32 v71, v70, v3
	v_exp_f32_e32 v71, v71
	v_cndmask_b32_e64 v80, 0, v72, s[34:35]
	v_cmp_lt_f32_e64 s[34:35], s81, v69
	v_pk_mul_f32 v[64:65], v[64:65], v[0:1] op_sel_hi:[1,0]
	v_cvt_pk_bf16_f32 v72, v81, v76
	v_cndmask_b32_e64 v83, 0, v68, s[34:35]
	v_cmp_lt_f32_e64 s[34:35], s81, v70
	v_add_u32_e32 v68, 0x6800, v79
	v_cvt_pk_bf16_f32 v73, v77, v78
	v_cndmask_b32_e64 v84, 0, v71, s[34:35]
	ds_read2_b64 v[68:71], v68 offset0:128 offset1:132
	v_cvt_pk_bf16_f32 v74, v82, v80
	v_cvt_pk_bf16_f32 v75, v83, v84
	v_pk_mul_f32 v[62:63], v[62:63], v[0:1] op_sel_hi:[1,0]
	v_pk_mul_f32 v[60:61], v[60:61], v[0:1] op_sel_hi:[1,0]
	s_waitcnt lgkmcnt(0)
	v_mfma_f32_16x16x32_bf16 v[64:67], v[68:71], v[72:75], v[64:67]
	v_add_u32_e32 v68, 0x9800, v79
	ds_read2_b64 v[68:71], v68 offset0:224 offset1:228
	v_cndmask_b32_e64 v79, v128, 32, vcc
	v_add_u32_e32 v85, v79, v129
	v_mad_u32_u24 v85, v85, s75, v155
	v_mfma_f32_16x16x32_bf16 v[60:63], v[86:89], v[72:75], v[60:63]
	ds_read_b128 v[86:89], v85 offset:9216
	v_pk_mul_f32 v[54:55], v[54:55], v[0:1] op_sel_hi:[1,0]
	v_pk_mul_f32 v[52:53], v[52:53], v[0:1] op_sel_hi:[1,0]
	v_pk_mul_f32 v[58:59], v[58:59], v[0:1] op_sel_hi:[1,0]
	v_pk_mul_f32 v[56:57], v[56:57], v[0:1] op_sel_hi:[1,0]
	s_waitcnt lgkmcnt(1)
	v_mfma_f32_16x16x32_bf16 v[52:55], v[68:71], v[72:75], v[52:55]
	ds_read_b128 v[68:71], v85 offset:9280
	v_mfma_f32_16x16x32_bf16 v[56:59], v[90:93], v[72:75], v[56:59]
	s_waitcnt lgkmcnt(1)
	v_mfma_f32_16x16x32_bf16 v[72:75], v[86:89], v[40:43], 0
	ds_read_b128 v[86:89], v85 offset:11520
	s_waitcnt lgkmcnt(1)
	v_mfma_f32_16x16x32_bf16 v[72:75], v[68:71], v[36:39], v[72:75]
	ds_read_b128 v[68:71], v85 offset:11584
	s_waitcnt lgkmcnt(1)
	v_mfma_f32_16x16x32_bf16 v[86:89], v[86:89], v[40:43], 0
	s_nop 4
	s_waitcnt lgkmcnt(0)
	v_mfma_f32_16x16x32_bf16 v[68:71], v[68:71], v[36:39], v[86:89]
	v_lshl_add_u32 v240, v2, 2, v137
	v_lshl_add_u32 v241, v2, 2, v138
	v_lshl_add_u32 v242, v2, 2, v139
	v_lshl_add_u32 v243, v2, 2, v140
	v_lshl_add_u32 v244, v2, 2, v141
	v_lshl_add_u32 v245, v2, 2, v142
	v_lshl_add_u32 v246, v2, 2, v143
	v_lshl_add_u32 v247, v2, 2, v144
	ds_read_b32 v240, v240 offset:45180
	ds_read_b32 v241, v241 offset:45180
	ds_read_b32 v242, v242 offset:45180
	ds_read_b32 v243, v243 offset:45180
	ds_read_b32 v244, v244 offset:45180
	ds_read_b32 v245, v245 offset:45180
	ds_read_b32 v246, v246 offset:45180
	ds_read_b32 v247, v247 offset:45180
	s_waitcnt lgkmcnt(0)
	v_add_f32_e32 v240, v72, v240
	v_add_f32_e32 v241, v73, v241
	v_add_f32_e32 v242, v74, v242
	v_add_f32_e32 v243, v75, v243
	v_add_f32_e32 v244, v68, v244
	v_add_f32_e32 v245, v69, v245
	v_add_f32_e32 v246, v70, v246
	v_add_f32_e32 v247, v71, v247
	v_cndmask_b32_e32 v85, v147, v72, vcc
	v_cndmask_b32_e64 v85, v85, v240, s[56:57]
	v_cndmask_b32_e32 v72, v147, v73, vcc
	v_cndmask_b32_e64 v72, v72, v241, s[58:59]
	v_cndmask_b32_e32 v73, v147, v74, vcc
	v_cndmask_b32_e64 v73, v73, v242, s[60:61]
	v_cndmask_b32_e32 v74, v147, v75, vcc
	v_cndmask_b32_e64 v74, v74, v243, s[62:63]
	v_cndmask_b32_e32 v75, v147, v68, vcc
	v_cndmask_b32_e64 v75, v75, v244, s[64:65]
	v_cndmask_b32_e32 v68, v147, v69, vcc
	v_cndmask_b32_e64 v68, v68, v245, s[66:67]
	v_cndmask_b32_e32 v69, v147, v70, vcc
	v_cndmask_b32_e64 v69, v69, v246, s[68:69]
	v_cndmask_b32_e32 v70, v147, v71, vcc
	v_cndmask_b32_e64 v70, v70, v247, s[70:71]
.LBB0_449:
	v_max3_f32 v2, v85, s80, v72
	v_max3_f32 v2, v2, v73, v74
	v_max3_f32 v2, v2, v75, v68
	v_max3_f32 v2, v2, v69, v70
	v_add_f32_e32 v71, 0, v81
	v_mov_b32_e32 v81, v2
	s_nop 1
	v_permlane16_swap_b32_e32 v2, v81
	v_add_f32_e32 v71, v76, v71
	v_add_f32_e32 v71, v77, v71
	v_add_f32_e32 v71, v78, v71
	v_add_f32_e32 v71, v82, v71
	s_waitcnt lgkmcnt(0)
	v_max_f32_e32 v76, v81, v81
	v_max_f32_e32 v2, v2, v76
	v_mov_b32_e32 v76, v2
	s_nop 1
	v_permlane32_swap_b32_e32 v2, v76
	v_add_f32_e32 v71, v80, v71
	v_add_f32_e32 v71, v83, v71
	v_add_f32_e32 v84, v84, v71
	v_fmac_f32_e32 v84, v152, v0
	s_waitcnt lgkmcnt(0)
	v_max3_f32 v153, v3, v2, v76
	v_sub_f32_e32 v2, v85, v153
	v_exp_f32_e32 v2, v2
	v_sub_f32_e32 v0, v3, v153
	v_sub_f32_e32 v3, v72, v153
	v_cmp_lt_f32_e64 s[34:35], s81, v85
	v_exp_f32_e32 v3, v3
	v_sub_f32_e32 v76, v74, v153
	v_cndmask_b32_e64 v2, 0, v2, s[34:35]
	v_cmp_lt_f32_e64 s[34:35], s81, v72
	v_sub_f32_e32 v72, v73, v153
	v_exp_f32_e32 v72, v72
	v_exp_f32_e32 v76, v76
	v_add_f32_e32 v71, 0, v2
	v_cndmask_b32_e64 v3, 0, v3, s[34:35]
	v_cmp_lt_f32_e64 s[34:35], s81, v73
	v_add_f32_e32 v71, v3, v71
	v_lshl_add_u32 v90, v79, 1, v136
	v_cndmask_b32_e64 v73, 0, v72, s[34:35]
	v_cmp_lt_f32_e64 s[34:35], s81, v74
	v_add_f32_e32 v71, v73, v71
	v_sub_f32_e32 v72, v68, v153
	v_cndmask_b32_e64 v74, 0, v76, s[34:35]
	v_add_f32_e32 v85, v74, v71
	v_sub_f32_e32 v71, v75, v153
	v_exp_f32_e32 v71, v71
	v_cmp_lt_f32_e64 s[34:35], s81, v75
	v_exp_f32_e32 v72, v72
	v_exp_f32_e32 v0, v0
	v_cndmask_b32_e64 v86, 0, v71, s[34:35]
	v_cmp_lt_f32_e64 s[34:35], s81, v68
	v_sub_f32_e32 v68, v69, v153
	v_exp_f32_e32 v68, v68
	v_sub_f32_e32 v71, v70, v153
	v_exp_f32_e32 v71, v71
	v_cndmask_b32_e64 v87, 0, v72, s[34:35]
	v_cmp_lt_f32_e64 s[34:35], s81, v69
	v_cvt_pk_bf16_f32 v72, v2, v3
	v_add_u32_e32 v2, 0x7800, v90
	v_cndmask_b32_e64 v88, 0, v68, s[34:35]
	v_cmp_lt_f32_e64 s[34:35], s81, v70
	v_add_u32_e32 v68, 0x6800, v90
	ds_read2_b64 v[76:79], v2 offset0:160 offset1:164
	v_cndmask_b32_e64 v89, 0, v71, s[34:35]
	ds_read2_b64 v[68:71], v68 offset0:128 offset1:132
	v_add_u32_e32 v2, 0x8800, v90
	v_pk_mul_f32 v[66:67], v[66:67], v[0:1] op_sel_hi:[1,0]
	v_pk_mul_f32 v[64:65], v[64:65], v[0:1] op_sel_hi:[1,0]
	v_cvt_pk_bf16_f32 v73, v73, v74
	v_cvt_pk_bf16_f32 v74, v86, v87
	v_cvt_pk_bf16_f32 v75, v88, v89
	ds_read2_b64 v[80:83], v2 offset0:192 offset1:196
	v_add_u32_e32 v2, 0x9800, v90
	s_waitcnt lgkmcnt(1)
	v_mfma_f32_16x16x32_bf16 v[64:67], v[68:71], v[72:75], v[64:67]
	ds_read2_b64 v[68:71], v2 offset0:224 offset1:228
	v_pk_mul_f32 v[62:63], v[62:63], v[0:1] op_sel_hi:[1,0]
	v_pk_mul_f32 v[60:61], v[60:61], v[0:1] op_sel_hi:[1,0]
	v_pk_mul_f32 v[58:59], v[58:59], v[0:1] op_sel_hi:[1,0]
	v_pk_mul_f32 v[56:57], v[56:57], v[0:1] op_sel_hi:[1,0]
	v_pk_mul_f32 v[54:55], v[54:55], v[0:1] op_sel_hi:[1,0]
	v_pk_mul_f32 v[52:53], v[52:53], v[0:1] op_sel_hi:[1,0]
	v_add_f32_e32 v2, v86, v85
	v_mfma_f32_16x16x32_bf16 v[60:63], v[76:79], v[72:75], v[60:63]
	v_add_f32_e32 v2, v87, v2
	v_add_f32_e32 v2, v88, v2
	v_add_f32_e32 v152, v89, v2
	s_waitcnt lgkmcnt(1)
	v_mfma_f32_16x16x32_bf16 v[56:59], v[80:83], v[72:75], v[56:59]
	v_cndmask_b32_e64 v2, 0, 1, vcc
	v_cmp_ne_u32_e64 s[34:35], 1, v2
	s_andn2_b64 vcc, exec, vcc
	s_waitcnt lgkmcnt(0)
	v_mfma_f32_16x16x32_bf16 v[52:55], v[68:71], v[72:75], v[52:55]
	v_fmac_f32_e32 v152, v84, v0
	s_cbranch_vccz .LBB0_460
	s_and_b64 vcc, exec, s[34:35]
	s_cbranch_vccnz .LBB0_409
	s_branch .LBB0_461

.LBB0_460:
	v_add_u32_e32 v0, v155, v134
	ds_read_b128 v[68:71], v0 offset:18432
	ds_read_b128 v[72:75], v0 offset:18496
	ds_read_b128 v[76:79], v0 offset:20736
	ds_read_b128 v[80:83], v0 offset:20800
	s_waitcnt lgkmcnt(3)
	v_mfma_f32_16x16x32_bf16 v[68:71], v[68:71], v[40:43], 0
	s_waitcnt lgkmcnt(1)
	v_mfma_f32_16x16x32_bf16 v[76:79], v[76:79], v[40:43], 0
	v_mfma_f32_16x16x32_bf16 v[68:71], v[72:75], v[36:39], v[68:71]
	s_waitcnt lgkmcnt(0)
	v_mfma_f32_16x16x32_bf16 v[72:75], v[80:83], v[36:39], v[76:79]
	s_nop 5
	v_max3_f32 v0, v68, s80, v69
	v_max3_f32 v0, v0, v70, v71
	v_max3_f32 v0, v0, v72, v73
	v_max3_f32 v0, v0, v74, v75
	v_mov_b32_e32 v2, v0
	s_nop 1
	v_permlane16_swap_b32_e32 v0, v2
	v_cmp_lt_f32_e32 vcc, s81, v68
	s_waitcnt lgkmcnt(0)
	v_max_f32_e32 v2, v2, v2
	v_max_f32_e32 v0, v0, v2
	v_mov_b32_e32 v2, v0
	s_nop 1
	v_permlane32_swap_b32_e32 v0, v2
	s_waitcnt lgkmcnt(0)
	v_max3_f32 v2, v153, v0, v2
	v_sub_f32_e32 v3, v68, v2
	v_sub_f32_e32 v76, v69, v2
	v_exp_f32_e32 v3, v3
	v_sub_f32_e32 v77, v70, v2
	v_exp_f32_e32 v76, v76
	v_sub_f32_e32 v78, v71, v2
	v_exp_f32_e32 v77, v77
	v_exp_f32_e32 v78, v78
	v_cndmask_b32_e32 v3, 0, v3, vcc
	v_cmp_lt_f32_e32 vcc, s81, v69
	v_add_f32_e32 v68, 0, v3
	v_sub_f32_e32 v79, v72, v2
	v_cndmask_b32_e32 v76, 0, v76, vcc
	v_cmp_lt_f32_e32 vcc, s81, v70
	v_add_f32_e32 v68, v76, v68
	v_sub_f32_e32 v80, v73, v2
	v_cndmask_b32_e32 v77, 0, v77, vcc
	v_cmp_lt_f32_e32 vcc, s81, v71
	v_exp_f32_e32 v79, v79
	v_add_f32_e32 v68, v77, v68
	v_cndmask_b32_e32 v78, 0, v78, vcc
	v_exp_f32_e32 v80, v80
	v_add_f32_e32 v84, v78, v68
	v_sub_f32_e32 v68, v74, v2
	v_exp_f32_e32 v68, v68
	v_sub_f32_e32 v69, v75, v2
	v_cmp_lt_f32_e32 vcc, s81, v72
	v_exp_f32_e32 v69, v69
	v_sub_f32_e32 v0, v153, v2
	v_cndmask_b32_e32 v85, 0, v79, vcc
	v_cmp_lt_f32_e32 vcc, s81, v73
	v_exp_f32_e32 v0, v0
	v_cvt_pk_bf16_f32 v72, v3, v76
	v_cndmask_b32_e32 v86, 0, v80, vcc
	v_cmp_lt_f32_e32 vcc, s81, v74
	v_add_u32_e32 v3, 0x7800, v136
	v_cvt_pk_bf16_f32 v73, v77, v78
	v_cndmask_b32_e32 v87, 0, v68, vcc
	v_cmp_lt_f32_e32 vcc, s81, v75
	v_add_u32_e32 v68, 0x6800, v136
	ds_read2_b64 v[76:79], v3 offset0:176 offset1:180
	v_cndmask_b32_e32 v88, 0, v69, vcc
	ds_read2_b64 v[68:71], v68 offset0:144 offset1:148
	v_add_u32_e32 v3, 0x8800, v136
	v_pk_mul_f32 v[66:67], v[66:67], v[0:1] op_sel_hi:[1,0]
	v_pk_mul_f32 v[64:65], v[64:65], v[0:1] op_sel_hi:[1,0]
	v_cvt_pk_bf16_f32 v74, v85, v86
	v_cvt_pk_bf16_f32 v75, v87, v88
	ds_read2_b64 v[80:83], v3 offset0:208 offset1:212
	v_add_u32_e32 v3, 0x9800, v136
	s_waitcnt lgkmcnt(1)
	v_mfma_f32_16x16x32_bf16 v[64:67], v[68:71], v[72:75], v[64:67]
	ds_read2_b64 v[68:71], v3 offset0:240 offset1:244
	v_add_f32_e32 v3, v85, v84
	v_pk_mul_f32 v[62:63], v[62:63], v[0:1] op_sel_hi:[1,0]
	v_pk_mul_f32 v[60:61], v[60:61], v[0:1] op_sel_hi:[1,0]
	v_pk_mul_f32 v[58:59], v[58:59], v[0:1] op_sel_hi:[1,0]
	v_pk_mul_f32 v[56:57], v[56:57], v[0:1] op_sel_hi:[1,0]
	v_pk_mul_f32 v[54:55], v[54:55], v[0:1] op_sel_hi:[1,0]
	v_pk_mul_f32 v[52:53], v[52:53], v[0:1] op_sel_hi:[1,0]
	v_add_f32_e32 v3, v86, v3
	v_mfma_f32_16x16x32_bf16 v[60:63], v[76:79], v[72:75], v[60:63]
	v_add_f32_e32 v3, v87, v3
	v_add_f32_e32 v3, v88, v3
	v_fmac_f32_e32 v3, v152, v0
	s_waitcnt lgkmcnt(1)
	v_mfma_f32_16x16x32_bf16 v[56:59], v[80:83], v[72:75], v[56:59]
	v_mov_b32_e32 v152, v3
	v_mov_b32_e32 v153, v2
	s_waitcnt lgkmcnt(0)
	v_mfma_f32_16x16x32_bf16 v[52:55], v[68:71], v[72:75], v[52:55]
	s_and_b64 vcc, exec, s[34:35]
	s_cbranch_vccnz .LBB0_409
.LBB0_461:
	v_add_u32_e32 v0, v155, v134
	ds_read_b128 v[68:71], v0 offset:23040
	ds_read_b128 v[72:75], v0 offset:23104
	ds_read_b128 v[76:79], v0 offset:25344
	ds_read_b128 v[80:83], v0 offset:25408
	s_waitcnt lgkmcnt(3)
	v_mfma_f32_16x16x32_bf16 v[68:71], v[68:71], v[40:43], 0
	s_waitcnt lgkmcnt(1)
	v_mfma_f32_16x16x32_bf16 v[76:79], v[76:79], v[40:43], 0
	v_mfma_f32_16x16x32_bf16 v[68:71], v[72:75], v[36:39], v[68:71]
	s_waitcnt lgkmcnt(0)
	v_mfma_f32_16x16x32_bf16 v[72:75], v[80:83], v[36:39], v[76:79]
	s_nop 5
	v_max3_f32 v0, v68, s80, v69
	v_max3_f32 v0, v0, v70, v71
	v_max3_f32 v0, v0, v72, v73
	v_max3_f32 v0, v0, v74, v75
	v_mov_b32_e32 v2, v0
	s_nop 1
	v_permlane16_swap_b32_e32 v0, v2
	v_cmp_lt_f32_e32 vcc, s81, v68
	s_waitcnt lgkmcnt(0)
	v_max_f32_e32 v2, v2, v2
	v_max_f32_e32 v0, v0, v2
	v_mov_b32_e32 v2, v0
	s_nop 1
	v_permlane32_swap_b32_e32 v0, v2
	s_waitcnt lgkmcnt(0)
	v_max3_f32 v2, v153, v0, v2
	v_sub_f32_e32 v3, v68, v2
	v_sub_f32_e32 v76, v69, v2
	v_exp_f32_e32 v3, v3
	v_sub_f32_e32 v77, v70, v2
	v_exp_f32_e32 v76, v76
	v_sub_f32_e32 v78, v71, v2
	v_exp_f32_e32 v77, v77
	v_exp_f32_e32 v78, v78
	v_cndmask_b32_e32 v3, 0, v3, vcc
	v_cmp_lt_f32_e32 vcc, s81, v69
	v_add_f32_e32 v68, 0, v3
	v_sub_f32_e32 v79, v72, v2
	v_cndmask_b32_e32 v76, 0, v76, vcc
	v_cmp_lt_f32_e32 vcc, s81, v70
	v_add_f32_e32 v68, v76, v68
	v_sub_f32_e32 v80, v73, v2
	v_cndmask_b32_e32 v77, 0, v77, vcc
	v_cmp_lt_f32_e32 vcc, s81, v71
	v_exp_f32_e32 v79, v79
	v_add_f32_e32 v68, v77, v68
	v_cndmask_b32_e32 v78, 0, v78, vcc
	v_exp_f32_e32 v80, v80
	v_add_f32_e32 v84, v78, v68
	v_sub_f32_e32 v68, v74, v2
	v_exp_f32_e32 v68, v68
	v_sub_f32_e32 v69, v75, v2
	v_cmp_lt_f32_e32 vcc, s81, v72
	v_exp_f32_e32 v69, v69
	v_sub_f32_e32 v0, v153, v2
	v_cndmask_b32_e32 v85, 0, v79, vcc
	v_cmp_lt_f32_e32 vcc, s81, v73
	v_exp_f32_e32 v0, v0
	v_cvt_pk_bf16_f32 v72, v3, v76
	v_cndmask_b32_e32 v86, 0, v80, vcc
	v_cmp_lt_f32_e32 vcc, s81, v74
	v_add_u32_e32 v3, 0x7800, v136
	v_cvt_pk_bf16_f32 v73, v77, v78
	v_cndmask_b32_e32 v87, 0, v68, vcc
	v_cmp_lt_f32_e32 vcc, s81, v75
	v_add_u32_e32 v68, 0x6800, v136
	ds_read2_b64 v[76:79], v3 offset0:184 offset1:188
	v_cndmask_b32_e32 v88, 0, v69, vcc
	ds_read2_b64 v[68:71], v68 offset0:152 offset1:156
	v_add_u32_e32 v3, 0x8800, v136
	v_pk_mul_f32 v[66:67], v[66:67], v[0:1] op_sel_hi:[1,0]
	v_pk_mul_f32 v[64:65], v[64:65], v[0:1] op_sel_hi:[1,0]
	v_cvt_pk_bf16_f32 v74, v85, v86
	v_cvt_pk_bf16_f32 v75, v87, v88
	ds_read2_b64 v[80:83], v3 offset0:216 offset1:220
	v_add_u32_e32 v3, 0x9800, v136
	s_waitcnt lgkmcnt(1)
	v_mfma_f32_16x16x32_bf16 v[64:67], v[68:71], v[72:75], v[64:67]
	ds_read2_b64 v[68:71], v3 offset0:248 offset1:252
	v_add_f32_e32 v3, v85, v84
	v_pk_mul_f32 v[62:63], v[62:63], v[0:1] op_sel_hi:[1,0]
	v_pk_mul_f32 v[60:61], v[60:61], v[0:1] op_sel_hi:[1,0]
	v_pk_mul_f32 v[58:59], v[58:59], v[0:1] op_sel_hi:[1,0]
	v_pk_mul_f32 v[56:57], v[56:57], v[0:1] op_sel_hi:[1,0]
	v_pk_mul_f32 v[54:55], v[54:55], v[0:1] op_sel_hi:[1,0]
	v_pk_mul_f32 v[52:53], v[52:53], v[0:1] op_sel_hi:[1,0]
	v_add_f32_e32 v3, v86, v3
	v_mfma_f32_16x16x32_bf16 v[60:63], v[76:79], v[72:75], v[60:63]
	v_add_f32_e32 v3, v87, v3
	v_add_f32_e32 v3, v88, v3
	v_fmac_f32_e32 v3, v152, v0
	s_waitcnt lgkmcnt(1)
	v_mfma_f32_16x16x32_bf16 v[56:59], v[80:83], v[72:75], v[56:59]
	v_mov_b32_e32 v152, v3
	v_mov_b32_e32 v153, v2
	s_waitcnt lgkmcnt(0)
	v_mfma_f32_16x16x32_bf16 v[52:55], v[68:71], v[72:75], v[52:55]
	s_branch .LBB0_409
